# RESID epilogue: 32 serialized flat load/wait/store round trips replaced by 14-deep batched global loads + in-place fma
# speedup vs baseline: 1.0101x; 1.0101x over previous
;     __device__ __forceinline__ void operator()(const f32x4 (&acc)[2][2][4][2], const Unit& u, int wr, int wc, int fr, int fq) const {
;     ...
;             const int mrow = is_ctx ? 4 : batch; const int col0 = u.pn * BM + wc * 32 + 8 * fq; const int gidx = aux & 15, ll = aux >> 4;
;             const float gs = gidx == 5 ? 1.f : 0.5f; float* f0 = (float*)(ws + WS_H);
;             const float* g = (const float*)(ws + WS_MOD) + (size_t)(ll * 5 + mrow) * NMOD + gidx * DM + col0;
;             f32x4 gv[2][2];
; #pragma unroll
;             for (int bj = 0; bj < 2; ++bj)
; #pragma unroll
;                 for (int n = 0; n < 2; ++n) gv[bj][n] = *(const f32x4*)(g + bj * 128 + 4 * n) * gs;
; #pragma unroll
;             for (int ai = 0; ai < 2; ++ai)
; #pragma unroll
;                 for (int m = 0; m < 4; ++m) { float* hp = f0 + (size_t)(row0 + ai * 128 + m * 16) * DM + col0;
; #pragma unroll
;                     for (int bj = 0; bj < 2; ++bj)
; #pragma unroll
;                         for (int n = 0; n < 2; ++n) { f32x4 h = *(f32x4*)(hp + bj * 128 + 4 * n); h += gv[bj][n] * acc[ai][bj][m][n]; *(f32x4*)(hp + bj * 128 + 4 * n) = h; }
;                     asm volatile("" ::: "memory"); }
.LBB0_437:
	s_andn2_b64 vcc, exec, s[10:11]
	s_cbranch_vccnz .LBB0_439
	s_and_b64 s[10:11], s[54:55], exec
	s_cselect_b32 s10, 4, s60
	s_lshl_b32 s11, s95, 8
	s_or_b32 s11, s11, s42
	v_lshl_add_u32 v128, v204, 3, s11
	v_readlane_b32 s11, v255, 5
	s_add_i32 s10, s10, s11
	s_mul_hi_i32 s11, s10, 0x9000
	s_mul_i32 s10, s10, 0x9000
	v_readlane_b32 s12, v255, 8
	s_add_u32 s10, s12, s10
	v_readlane_b32 s12, v255, 9
	v_ashrrev_i32_e32 v129, 31, v128
	s_addc_u32 s11, s12, s11
	v_lshlrev_b64 v[172:173], 2, v[128:129]
	global_load_dwordx4 v[128:131], v172, s[10:11]
	global_load_dwordx4 v[132:135], v172, s[10:11] offset:16
	global_load_dwordx4 v[136:139], v172, s[10:11] offset:512
	global_load_dwordx4 v[140:143], v172, s[10:11] offset:528
	v_lshl_add_u32 v168, v166, 12, v172
	s_mov_b64 s[12:13], s[0:1]
	s_mov_b64 s[14:15], s[0:1]
	global_load_dwordx4 v[206:209], v168, s[12:13]
	global_load_dwordx4 v[210:213], v168, s[12:13] offset:16
	global_load_dwordx4 v[214:217], v168, s[12:13] offset:512
	global_load_dwordx4 v[218:221], v168, s[12:13] offset:528
	s_add_u32 s12, s12, 0x10000
	s_addc_u32 s13, s13, 0
	global_load_dwordx4 v[222:225], v168, s[12:13]
	global_load_dwordx4 v[226:229], v168, s[12:13] offset:16
	global_load_dwordx4 v[230:233], v168, s[12:13] offset:512
	global_load_dwordx4 v[234:237], v168, s[12:13] offset:528
	s_add_u32 s12, s12, 0x10000
	s_addc_u32 s13, s13, 0
	global_load_dwordx4 v[238:241], v168, s[12:13]
	global_load_dwordx4 v[242:245], v168, s[12:13] offset:16
	global_load_dwordx4 v[170:173], v168, s[12:13] offset:512
	global_load_dwordx4 v[174:177], v168, s[12:13] offset:528
	s_add_u32 s12, s12, 0x10000
	s_addc_u32 s13, s13, 0
	global_load_dwordx4 v[178:181], v168, s[12:13]
	global_load_dwordx4 v[182:185], v168, s[12:13] offset:16
	s_waitcnt vmcnt(14)
	v_pk_mul_f32 v[128:129], v[160:161], v[128:129]
	v_pk_mul_f32 v[130:131], v[160:161], v[130:131]
	v_pk_mul_f32 v[132:133], v[160:161], v[132:133]
	v_pk_mul_f32 v[134:135], v[160:161], v[134:135]
	v_pk_mul_f32 v[136:137], v[160:161], v[136:137]
	v_pk_mul_f32 v[138:139], v[160:161], v[138:139]
	v_pk_mul_f32 v[140:141], v[160:161], v[140:141]
	v_pk_mul_f32 v[142:143], v[160:161], v[142:143]
	s_waitcnt vmcnt(13)
	v_pk_fma_f32 v[124:125], v[124:125], v[128:129], v[206:207]
	v_pk_fma_f32 v[126:127], v[126:127], v[130:131], v[208:209]
	global_store_dwordx4 v168, v[124:127], s[14:15]
	global_load_dwordx4 v[206:209], v168, s[12:13] offset:512
	s_waitcnt vmcnt(14)
	v_pk_fma_f32 v[120:121], v[120:121], v[132:133], v[210:211]
	v_pk_fma_f32 v[122:123], v[122:123], v[134:135], v[212:213]
	global_store_dwordx4 v168, v[120:123], s[14:15] offset:16
	global_load_dwordx4 v[210:213], v168, s[12:13] offset:528
	s_waitcnt vmcnt(15)
	v_pk_fma_f32 v[116:117], v[116:117], v[136:137], v[214:215]
	v_pk_fma_f32 v[118:119], v[118:119], v[138:139], v[216:217]
	global_store_dwordx4 v168, v[116:119], s[14:15] offset:512
	s_add_u32 s12, s12, 0x50000
	s_addc_u32 s13, s13, 0
	global_load_dwordx4 v[214:217], v168, s[12:13]
	s_waitcnt vmcnt(16)
	v_pk_fma_f32 v[112:113], v[112:113], v[140:141], v[218:219]
	v_pk_fma_f32 v[114:115], v[114:115], v[142:143], v[220:221]
	global_store_dwordx4 v168, v[112:115], s[14:15] offset:528
	global_load_dwordx4 v[218:221], v168, s[12:13] offset:16
	s_waitcnt vmcnt(17)
	v_pk_fma_f32 v[108:109], v[108:109], v[128:129], v[222:223]
	v_pk_fma_f32 v[110:111], v[110:111], v[130:131], v[224:225]
	s_add_u32 s14, s14, 0x10000
	s_addc_u32 s15, s15, 0
	global_store_dwordx4 v168, v[108:111], s[14:15]
	global_load_dwordx4 v[222:225], v168, s[12:13] offset:512
	s_waitcnt vmcnt(18)
	v_pk_fma_f32 v[104:105], v[104:105], v[132:133], v[226:227]
	v_pk_fma_f32 v[106:107], v[106:107], v[134:135], v[228:229]
	global_store_dwordx4 v168, v[104:107], s[14:15] offset:16
	global_load_dwordx4 v[226:229], v168, s[12:13] offset:528
	s_waitcnt vmcnt(19)
	v_pk_fma_f32 v[100:101], v[100:101], v[136:137], v[230:231]
	v_pk_fma_f32 v[102:103], v[102:103], v[138:139], v[232:233]
	global_store_dwordx4 v168, v[100:103], s[14:15] offset:512
	s_add_u32 s12, s12, 0x10000
	s_addc_u32 s13, s13, 0
	global_load_dwordx4 v[230:233], v168, s[12:13]
	s_waitcnt vmcnt(20)
	v_pk_fma_f32 v[96:97], v[96:97], v[140:141], v[234:235]
	v_pk_fma_f32 v[98:99], v[98:99], v[142:143], v[236:237]
	global_store_dwordx4 v168, v[96:99], s[14:15] offset:528
	global_load_dwordx4 v[234:237], v168, s[12:13] offset:16
	s_waitcnt vmcnt(21)
	v_pk_fma_f32 v[92:93], v[92:93], v[128:129], v[238:239]
	v_pk_fma_f32 v[94:95], v[94:95], v[130:131], v[240:241]
	s_add_u32 s14, s14, 0x10000
	s_addc_u32 s15, s15, 0
	global_store_dwordx4 v168, v[92:95], s[14:15]
	global_load_dwordx4 v[238:241], v168, s[12:13] offset:512
	s_waitcnt vmcnt(22)
	v_pk_fma_f32 v[88:89], v[88:89], v[132:133], v[242:243]
	v_pk_fma_f32 v[90:91], v[90:91], v[134:135], v[244:245]
	global_store_dwordx4 v168, v[88:91], s[14:15] offset:16
	global_load_dwordx4 v[242:245], v168, s[12:13] offset:528
	s_waitcnt vmcnt(23)
;     __device__ __forceinline__ void operator()(const f32x4 (&acc)[2][2][4][2], const Unit& u, int wr, int wc, int fr, int fq) const {
;     ...
;             for (int ai = 0; ai < 2; ++ai)
; #pragma unroll
;                 for (int m = 0; m < 4; ++m) { float* hp = f0 + (size_t)(row0 + ai * 128 + m * 16) * DM + col0;
; #pragma unroll
;                     for (int bj = 0; bj < 2; ++bj)
; #pragma unroll
;                         for (int n = 0; n < 2; ++n) { f32x4 h = *(f32x4*)(hp + bj * 128 + 4 * n); h += gv[bj][n] * acc[ai][bj][m][n]; *(f32x4*)(hp + bj * 128 + 4 * n) = h; }
;                     asm volatile("" ::: "memory"); }
	v_pk_fma_f32 v[84:85], v[84:85], v[136:137], v[170:171]
	v_pk_fma_f32 v[86:87], v[86:87], v[138:139], v[172:173]
	global_store_dwordx4 v168, v[84:87], s[14:15] offset:512
	s_add_u32 s12, s12, 0x10000
	s_addc_u32 s13, s13, 0
	global_load_dwordx4 v[170:173], v168, s[12:13]
	s_waitcnt vmcnt(24)
	v_pk_fma_f32 v[80:81], v[80:81], v[140:141], v[174:175]
	v_pk_fma_f32 v[82:83], v[82:83], v[142:143], v[176:177]
	global_store_dwordx4 v168, v[80:83], s[14:15] offset:528
	global_load_dwordx4 v[174:177], v168, s[12:13] offset:16
	s_waitcnt vmcnt(25)
	v_pk_fma_f32 v[76:77], v[76:77], v[128:129], v[178:179]
	v_pk_fma_f32 v[78:79], v[78:79], v[130:131], v[180:181]
	s_add_u32 s14, s14, 0x10000
	s_addc_u32 s15, s15, 0
	global_store_dwordx4 v168, v[76:79], s[14:15]
	global_load_dwordx4 v[178:181], v168, s[12:13] offset:512
	s_waitcnt vmcnt(26)
	v_pk_fma_f32 v[72:73], v[72:73], v[132:133], v[182:183]
	v_pk_fma_f32 v[74:75], v[74:75], v[134:135], v[184:185]
	global_store_dwordx4 v168, v[72:75], s[14:15] offset:16
	global_load_dwordx4 v[182:185], v168, s[12:13] offset:528
	s_waitcnt vmcnt(26)
	v_pk_fma_f32 v[68:69], v[68:69], v[136:137], v[206:207]
	v_pk_fma_f32 v[70:71], v[70:71], v[138:139], v[208:209]
	global_store_dwordx4 v168, v[68:71], s[14:15] offset:512
	s_add_u32 s12, s12, 0x10000
	s_addc_u32 s13, s13, 0
	global_load_dwordx4 v[206:209], v168, s[12:13]
	s_waitcnt vmcnt(26)
	v_pk_fma_f32 v[64:65], v[64:65], v[140:141], v[210:211]
	v_pk_fma_f32 v[66:67], v[66:67], v[142:143], v[212:213]
	global_store_dwordx4 v168, v[64:67], s[14:15] offset:528
	global_load_dwordx4 v[210:213], v168, s[12:13] offset:16
	s_waitcnt vmcnt(26)
	v_pk_fma_f32 v[60:61], v[60:61], v[128:129], v[214:215]
	v_pk_fma_f32 v[62:63], v[62:63], v[130:131], v[216:217]
	s_add_u32 s14, s14, 0x50000
	s_addc_u32 s15, s15, 0
	global_store_dwordx4 v168, v[60:63], s[14:15]
	global_load_dwordx4 v[214:217], v168, s[12:13] offset:512
	s_waitcnt vmcnt(26)
	v_pk_fma_f32 v[56:57], v[56:57], v[132:133], v[218:219]
	v_pk_fma_f32 v[58:59], v[58:59], v[134:135], v[220:221]
	global_store_dwordx4 v168, v[56:59], s[14:15] offset:16
	global_load_dwordx4 v[218:221], v168, s[12:13] offset:528
	s_waitcnt vmcnt(26)
	v_pk_fma_f32 v[52:53], v[52:53], v[136:137], v[222:223]
	v_pk_fma_f32 v[54:55], v[54:55], v[138:139], v[224:225]
	global_store_dwordx4 v168, v[52:55], s[14:15] offset:512
	s_waitcnt vmcnt(25)
	v_pk_fma_f32 v[48:49], v[48:49], v[140:141], v[226:227]
	v_pk_fma_f32 v[50:51], v[50:51], v[142:143], v[228:229]
	global_store_dwordx4 v168, v[48:51], s[14:15] offset:528
	s_waitcnt vmcnt(24)
	v_pk_fma_f32 v[44:45], v[44:45], v[128:129], v[230:231]
	v_pk_fma_f32 v[46:47], v[46:47], v[130:131], v[232:233]
	s_add_u32 s14, s14, 0x10000
	s_addc_u32 s15, s15, 0
	global_store_dwordx4 v168, v[44:47], s[14:15]
	s_waitcnt vmcnt(23)
	v_pk_fma_f32 v[40:41], v[40:41], v[132:133], v[234:235]
	v_pk_fma_f32 v[42:43], v[42:43], v[134:135], v[236:237]
	global_store_dwordx4 v168, v[40:43], s[14:15] offset:16
	s_waitcnt vmcnt(22)
	v_pk_fma_f32 v[36:37], v[36:37], v[136:137], v[238:239]
	v_pk_fma_f32 v[38:39], v[38:39], v[138:139], v[240:241]
	global_store_dwordx4 v168, v[36:39], s[14:15] offset:512
	s_waitcnt vmcnt(21)
	v_pk_fma_f32 v[32:33], v[32:33], v[140:141], v[242:243]
	v_pk_fma_f32 v[34:35], v[34:35], v[142:143], v[244:245]
	global_store_dwordx4 v168, v[32:35], s[14:15] offset:528
	s_waitcnt vmcnt(20)
	v_pk_fma_f32 v[28:29], v[28:29], v[128:129], v[170:171]
	v_pk_fma_f32 v[30:31], v[30:31], v[130:131], v[172:173]
	s_add_u32 s14, s14, 0x10000
	s_addc_u32 s15, s15, 0
	global_store_dwordx4 v168, v[28:31], s[14:15]
	s_waitcnt vmcnt(19)
	v_pk_fma_f32 v[24:25], v[24:25], v[132:133], v[174:175]
	v_pk_fma_f32 v[26:27], v[26:27], v[134:135], v[176:177]
	global_store_dwordx4 v168, v[24:27], s[14:15] offset:16
	s_waitcnt vmcnt(18)
	v_pk_fma_f32 v[20:21], v[20:21], v[136:137], v[178:179]
	v_pk_fma_f32 v[22:23], v[22:23], v[138:139], v[180:181]
	global_store_dwordx4 v168, v[20:23], s[14:15] offset:512
	s_waitcnt vmcnt(17)
	v_pk_fma_f32 v[16:17], v[16:17], v[140:141], v[182:183]
	v_pk_fma_f32 v[18:19], v[18:19], v[142:143], v[184:185]
	global_store_dwordx4 v168, v[16:19], s[14:15] offset:528
	s_waitcnt vmcnt(16)
	v_pk_fma_f32 v[12:13], v[12:13], v[128:129], v[206:207]
	v_pk_fma_f32 v[14:15], v[14:15], v[130:131], v[208:209]
	s_add_u32 s14, s14, 0x10000
	s_addc_u32 s15, s15, 0
	global_store_dwordx4 v168, v[12:15], s[14:15]
	s_waitcnt vmcnt(15)
	v_pk_fma_f32 v[8:9], v[8:9], v[132:133], v[210:211]
	v_pk_fma_f32 v[10:11], v[10:11], v[134:135], v[212:213]
	global_store_dwordx4 v168, v[8:11], s[14:15] offset:16
	s_waitcnt vmcnt(14)
	v_pk_fma_f32 v[4:5], v[4:5], v[136:137], v[214:215]
	v_pk_fma_f32 v[6:7], v[6:7], v[138:139], v[216:217]
	global_store_dwordx4 v168, v[4:7], s[14:15] offset:512
	s_waitcnt vmcnt(13)
	v_pk_fma_f32 v[0:1], v[0:1], v[140:141], v[218:219]
	v_pk_fma_f32 v[2:3], v[2:3], v[142:143], v[220:221]
	global_store_dwordx4 v168, v[0:3], s[14:15] offset:528
